# v116 plus prologue silu(cvec) table loop with its eight loads issued before the compute and LDS writes
# speedup vs baseline: 1.0056x; 1.0056x over previous
; #define LAS __attribute__((address_space(3)))
; __device__ __forceinline__ float sigmoidf_(float x) { return __builtin_amdgcn_rcpf(1.0f + __expf(-x)); }
; __device__ __forceinline__ void p0_prologue(const Frame& F) {
;     ...
;         LAS float* sv = (LAS float*)F.lds;
;         LAS float* red = (LAS float*)(F.lds + 16384);
;         for (int i = F.tid; i < 2 * D; i += NTHREADS) { const float x = (i < D) ? F.in[I_C][i] : F.in[I_CCTX][i - D]; sv[i] = x * sigmoidf_(x); }
.LBB0_73:
	s_mov_b64 s[24:25], 0
	s_mov_b64 s[26:27], 0
	s_mov_b64 s[28:29], 0
	s_mov_b64 s[30:31], 0
	s_mov_b64 s[32:33], 0
	s_mov_b64 s[34:35], 0
	s_mov_b64 s[52:53], 0
	s_mov_b64 s[54:55], 0
	s_mov_b64 s[24:25], exec
	v_lshl_add_u64 v[8:9], v[4:5], 2, s[42:43]
	v_lshl_add_u64 v[8:9], v[8:9], 0, s[6:7]
	v_cmp_gt_i32_e32 vcc, s2, v4
	s_nop 1
	v_cndmask_b32_e32 v9, v9, v3, vcc
	v_cndmask_b32_e32 v8, v8, v2, vcc
	global_load_dword v70, v[8:9], off
	v_cmp_ge_i32_e32 vcc, s3, v4
	v_add_u32_e32 v4, 0x200, v4
	v_lshl_add_u64 v[2:3], v[2:3], 0, s[8:9]
	s_and_b64 exec, exec, vcc
	s_cbranch_execz .Lmy_sl_ld_done
	s_mov_b64 s[26:27], exec
	v_lshl_add_u64 v[8:9], v[4:5], 2, s[42:43]
	v_lshl_add_u64 v[8:9], v[8:9], 0, s[6:7]
	v_cmp_gt_i32_e32 vcc, s2, v4
	s_nop 1
	v_cndmask_b32_e32 v9, v9, v3, vcc
	v_cndmask_b32_e32 v8, v8, v2, vcc
	global_load_dword v71, v[8:9], off
	v_cmp_ge_i32_e32 vcc, s3, v4
	v_add_u32_e32 v4, 0x200, v4
	v_lshl_add_u64 v[2:3], v[2:3], 0, s[8:9]
	s_and_b64 exec, exec, vcc
	s_cbranch_execz .Lmy_sl_ld_done
	s_mov_b64 s[28:29], exec
	v_lshl_add_u64 v[8:9], v[4:5], 2, s[42:43]
	v_lshl_add_u64 v[8:9], v[8:9], 0, s[6:7]
	v_cmp_gt_i32_e32 vcc, s2, v4
	s_nop 1
	v_cndmask_b32_e32 v9, v9, v3, vcc
	v_cndmask_b32_e32 v8, v8, v2, vcc
	global_load_dword v72, v[8:9], off
	v_cmp_ge_i32_e32 vcc, s3, v4
	v_add_u32_e32 v4, 0x200, v4
	v_lshl_add_u64 v[2:3], v[2:3], 0, s[8:9]
	s_and_b64 exec, exec, vcc
	s_cbranch_execz .Lmy_sl_ld_done
	s_mov_b64 s[30:31], exec
	v_lshl_add_u64 v[8:9], v[4:5], 2, s[42:43]
	v_lshl_add_u64 v[8:9], v[8:9], 0, s[6:7]
	v_cmp_gt_i32_e32 vcc, s2, v4
	s_nop 1
	v_cndmask_b32_e32 v9, v9, v3, vcc
	v_cndmask_b32_e32 v8, v8, v2, vcc
	global_load_dword v73, v[8:9], off
	v_cmp_ge_i32_e32 vcc, s3, v4
	v_add_u32_e32 v4, 0x200, v4
	v_lshl_add_u64 v[2:3], v[2:3], 0, s[8:9]
	s_and_b64 exec, exec, vcc
	s_cbranch_execz .Lmy_sl_ld_done
	s_mov_b64 s[32:33], exec
	v_lshl_add_u64 v[8:9], v[4:5], 2, s[42:43]
	v_lshl_add_u64 v[8:9], v[8:9], 0, s[6:7]
	v_cmp_gt_i32_e32 vcc, s2, v4
	s_nop 1
	v_cndmask_b32_e32 v9, v9, v3, vcc
	v_cndmask_b32_e32 v8, v8, v2, vcc
	global_load_dword v74, v[8:9], off
	v_cmp_ge_i32_e32 vcc, s3, v4
	v_add_u32_e32 v4, 0x200, v4
	v_lshl_add_u64 v[2:3], v[2:3], 0, s[8:9]
	s_and_b64 exec, exec, vcc
	s_cbranch_execz .Lmy_sl_ld_done
	s_mov_b64 s[34:35], exec
	v_lshl_add_u64 v[8:9], v[4:5], 2, s[42:43]
	v_lshl_add_u64 v[8:9], v[8:9], 0, s[6:7]
	v_cmp_gt_i32_e32 vcc, s2, v4
	s_nop 1
	v_cndmask_b32_e32 v9, v9, v3, vcc
	v_cndmask_b32_e32 v8, v8, v2, vcc
	global_load_dword v75, v[8:9], off
	v_cmp_ge_i32_e32 vcc, s3, v4
	v_add_u32_e32 v4, 0x200, v4
	v_lshl_add_u64 v[2:3], v[2:3], 0, s[8:9]
	s_and_b64 exec, exec, vcc
	s_cbranch_execz .Lmy_sl_ld_done
	s_mov_b64 s[52:53], exec
	v_lshl_add_u64 v[8:9], v[4:5], 2, s[42:43]
	v_lshl_add_u64 v[8:9], v[8:9], 0, s[6:7]
	v_cmp_gt_i32_e32 vcc, s2, v4
	s_nop 1
	v_cndmask_b32_e32 v9, v9, v3, vcc
	v_cndmask_b32_e32 v8, v8, v2, vcc
	global_load_dword v76, v[8:9], off
	v_cmp_ge_i32_e32 vcc, s3, v4
	v_add_u32_e32 v4, 0x200, v4
	v_lshl_add_u64 v[2:3], v[2:3], 0, s[8:9]
	s_and_b64 exec, exec, vcc
	s_cbranch_execz .Lmy_sl_ld_done
	s_mov_b64 s[54:55], exec
	v_lshl_add_u64 v[8:9], v[4:5], 2, s[42:43]
	v_lshl_add_u64 v[8:9], v[8:9], 0, s[6:7]
	v_cmp_gt_i32_e32 vcc, s2, v4
	s_nop 1
	v_cndmask_b32_e32 v9, v9, v3, vcc
	v_cndmask_b32_e32 v8, v8, v2, vcc
	global_load_dword v77, v[8:9], off
	v_cmp_ge_i32_e32 vcc, s3, v4
	v_add_u32_e32 v4, 0x200, v4
	v_lshl_add_u64 v[2:3], v[2:3], 0, s[8:9]
	s_and_b64 exec, exec, vcc
.Lmy_sl_ld_done:
	s_mov_b64 s[4:5], exec
	s_waitcnt vmcnt(0)
	s_mov_b64 exec, s[24:25]
	v_mul_f32_e32 v120, 0xbfb8aa3b, v70
	v_exp_f32_e32 v120, v120
	s_nop 0
	v_add_f32_e32 v121, 1.0, v120
	v_rcp_f32_e32 v120, v121
	s_nop 0
	v_mul_f32_e32 v121, v70, v120
	ds_write_b32 v6, v121
	s_mov_b64 exec, s[26:27]
	s_cbranch_execz .Lmy_sl_st_done
	v_mul_f32_e32 v120, 0xbfb8aa3b, v71
	v_exp_f32_e32 v120, v120
	s_nop 0
	v_add_f32_e32 v121, 1.0, v120
	v_rcp_f32_e32 v120, v121
	s_nop 0
	v_mul_f32_e32 v121, v71, v120
	ds_write_b32 v6, v121 offset:2048
	s_mov_b64 exec, s[28:29]
	s_cbranch_execz .Lmy_sl_st_done
	v_mul_f32_e32 v120, 0xbfb8aa3b, v72
	v_exp_f32_e32 v120, v120
	s_nop 0
	v_add_f32_e32 v121, 1.0, v120
	v_rcp_f32_e32 v120, v121
	s_nop 0
	v_mul_f32_e32 v121, v72, v120
	ds_write_b32 v6, v121 offset:4096
	s_mov_b64 exec, s[30:31]
	s_cbranch_execz .Lmy_sl_st_done
	v_mul_f32_e32 v120, 0xbfb8aa3b, v73
	v_exp_f32_e32 v120, v120
	s_nop 0
	v_add_f32_e32 v121, 1.0, v120
	v_rcp_f32_e32 v120, v121
	s_nop 0
	v_mul_f32_e32 v121, v73, v120
	ds_write_b32 v6, v121 offset:6144
	s_mov_b64 exec, s[32:33]
	s_cbranch_execz .Lmy_sl_st_done
	v_mul_f32_e32 v120, 0xbfb8aa3b, v74
	v_exp_f32_e32 v120, v120
	s_nop 0
	v_add_f32_e32 v121, 1.0, v120
	v_rcp_f32_e32 v120, v121
	s_nop 0
	v_mul_f32_e32 v121, v74, v120
	ds_write_b32 v6, v121 offset:8192
	s_mov_b64 exec, s[34:35]
	s_cbranch_execz .Lmy_sl_st_done
	v_mul_f32_e32 v120, 0xbfb8aa3b, v75
	v_exp_f32_e32 v120, v120
	s_nop 0
	v_add_f32_e32 v121, 1.0, v120
	v_rcp_f32_e32 v120, v121
	s_nop 0
	v_mul_f32_e32 v121, v75, v120
	ds_write_b32 v6, v121 offset:10240
	s_mov_b64 exec, s[52:53]
	s_cbranch_execz .Lmy_sl_st_done
	v_mul_f32_e32 v120, 0xbfb8aa3b, v76
	v_exp_f32_e32 v120, v120
	s_nop 0
	v_add_f32_e32 v121, 1.0, v120
	v_rcp_f32_e32 v120, v121
	s_nop 0
	v_mul_f32_e32 v121, v76, v120
	ds_write_b32 v6, v121 offset:12288
	s_mov_b64 exec, s[54:55]
	s_cbranch_execz .Lmy_sl_st_done
	v_mul_f32_e32 v120, 0xbfb8aa3b, v77
	v_exp_f32_e32 v120, v120
	s_nop 0
	v_add_f32_e32 v121, 1.0, v120
	v_rcp_f32_e32 v120, v121
	s_nop 0
	v_mul_f32_e32 v121, v77, v120
	ds_write_b32 v6, v121 offset:14336
.Lmy_sl_st_done:
	s_mov_b64 exec, s[4:5]
	v_add_u32_e32 v6, 0x4000, v6
	s_cbranch_execnz .LBB0_73
